# PW1 with R0=28672: phase 0 streams 28672 rows (waves 4-7), phase 1 streams 20480 rows under the two-pass weight-product unit
# baseline (speedup 1.0000x reference)
; __device__ void p0_xconv(const Args& a) {
;     f16* XH = (f16*)(a.ws + WS_XH); float* SS = (float*)(a.ws + WS_SS);
;     int tid_ = threadIdx.x; asm volatile("" : "+v"(tid_));
;     const int lane = tid_ & 63, wv = tid_ >> 6;
;     const int nwv = (int)gridDim.x * 8;
;     for (int row0 = (int)blockIdx.x * 8 + wv; row0 < MROWS; row0 += 4 * nwv) {
;         f32x4 v[4][4];
; #pragma unroll
;         for (int r = 0; r < 4; ++r) {
;             const int row = row0 + r * nwv;
;             if (row < MROWS) {
;                 const float* src = (row < ROWS_PROMPT) ? a.x_prompt + (size_t)row * DM : a.x_sample + (size_t)(row - ROWS_PROMPT) * DM;
; #pragma unroll
;                 for (int i = 0; i < 4; ++i) v[r][i] = __builtin_nontemporal_load((const f32x4*)(src + i * 256 + lane * 4));
;             }
;         }
.Lws_x:
	v_writelane_b32 v255, s14, 10
	v_writelane_b32 v255, s15, 11
	v_writelane_b32 v255, s20, 12
	v_writelane_b32 v255, s21, 13
	v_writelane_b32 v255, s22, 14
	v_writelane_b32 v255, s23, 15
	v_mov_b32_e32 v1, v0
	s_mov_b32 s3, 0x7000
	v_ashrrev_i32_e32 v2, 6, v1
	v_lshl_add_u32 v78, s2, 2, v2
	v_add_u32_e32 v78, -4, v78
	v_cmp_gt_i32_e32 vcc, s3, v78
	s_and_saveexec_b64 s[20:21], vcc
	s_cbranch_execz .Lxc_111
	v_and_b32_e32 v1, 63, v1
	v_mov_b32_e32 v67, 0
	v_lshlrev_b32_e32 v66, 2, v1
	v_lshlrev_b32_e32 v2, 3, v1
	v_mov_b32_e32 v3, v67
	s_movk_i32 s36, 0x80
	v_lshl_add_u64 v[68:69], s[40:41], 0, v[2:3]
	v_lshl_add_u64 v[2:3], s[40:41], 0, v[66:67]
	s_mov_b64 s[4:5], 0x1f800000
	v_cmp_gt_u32_e32 vcc, 16, v1
	v_lshl_add_u64 v[70:71], v[2:3], 0, s[4:5]
	v_cmp_eq_u32_e64 s[4:5], 0, v1
	v_mbcnt_lo_u32_b32 v1, -1, 0
	v_mbcnt_hi_u32_b32 v2, -1, v1
	v_and_b32_e32 v1, 64, v2
	v_add_u32_e32 v3, 64, v1
	v_xor_b32_e32 v1, 1, v2
	v_cmp_lt_i32_e64 s[6:7], v1, v3
	v_xor_b32_e32 v4, 2, v2
	s_waitcnt lgkmcnt(0)
	s_lshl_b32 s9, s36, 3
	v_cndmask_b32_e64 v1, v2, v1, s[6:7]
	v_cmp_lt_i32_e64 s[6:7], v4, v3
	s_add_i32 s44, s9, s9
	v_lshlrev_b32_e32 v1, 2, v1
	v_cndmask_b32_e64 v4, v2, v4, s[6:7]
	v_lshlrev_b32_e32 v80, 2, v4
	v_xor_b32_e32 v4, 4, v2
	v_cmp_lt_i32_e64 s[6:7], v4, v3
	s_lshl_b32 s33, s36, 4
	s_mul_i32 s36, s36, 24
	v_cndmask_b32_e64 v4, v2, v4, s[6:7]
	v_lshlrev_b32_e32 v81, 2, v4
	v_xor_b32_e32 v4, 8, v2
	v_cmp_lt_i32_e64 s[6:7], v4, v3
	s_mov_b64 s[22:23], 0
	s_movk_i32 s37, 0x4000
	v_cndmask_b32_e64 v4, v2, v4, s[6:7]
	v_lshlrev_b32_e32 v82, 2, v4
	v_xor_b32_e32 v4, 16, v2
	v_cmp_lt_i32_e64 s[6:7], v4, v3
	v_mov_b32_e32 v85, s19
	v_mov_b32_e32 v86, s17
	v_cndmask_b32_e64 v4, v2, v4, s[6:7]
	v_lshlrev_b32_e32 v83, 2, v4
	v_xor_b32_e32 v4, 32, v2
	v_cmp_lt_i32_e64 s[6:7], v4, v3
	v_mov_b32_e32 v87, s18
	v_mov_b32_e32 v88, s16
	v_cndmask_b32_e64 v2, v2, v4, s[6:7]
	v_lshlrev_b32_e32 v84, 2, v2
	v_lshlrev_b32_e32 v66, 2, v66
	s_add_i32 s44, s44, s9
	s_mov_b32 s45, 0x6fff
	s_branch .Lxc_94

; __device__ void p0_xconv(const Args& a) {
;     ...
;     for (int row0 = (int)blockIdx.x * 8 + wv; row0 < MROWS; row0 += 4 * nwv) {
;         f32x4 v[4][4];
; #pragma unroll
;         for (int r = 0; r < 4; ++r) {
;             const int row = row0 + r * nwv;
;             if (row < MROWS) {
;                 const float* src = (row < ROWS_PROMPT) ? a.x_prompt + (size_t)row * DM : a.x_sample + (size_t)(row - ROWS_PROMPT) * DM;
; #pragma unroll
;                 for (int i = 0; i < 4; ++i) v[r][i] = __builtin_nontemporal_load((const f32x4*)(src + i * 256 + lane * 4));
;             }
;         }
; #pragma unroll
;         for (int r = 0; r < 4; ++r) {
;             const int row = row0 + r * nwv;
;             if (row < MROWS) {
;                 float ss = 0.f;
; #pragma unroll
;                 for (int i = 0; i < 4; ++i) {
;                     const f32x4 x = v[r][i];
;                     ss += (x[0] * x[0] + x[1] * x[1]) + (x[2] * x[2] + x[3] * x[3]);
;                     f16x4 h; h[0] = (f16)x[0]; h[1] = (f16)x[1]; h[2] = (f16)x[2]; h[3] = (f16)x[3];
;                     *(f16x4*)(XH + (size_t)row * DM + i * 256 + lane * 4) = h;
;                 }
.Lpw_x:
	s_barrier
	v_and_b32_e32 v136, 63, v0
	v_lshrrev_b32_e32 v137, 6, v0
	s_nop 0
	v_readfirstlane_b32 s3, v137
	s_nop 3
	s_lshl_b32 s4, s2, 2
	s_add_i32 s3, s3, s4
	s_add_i32 s3, s3, -4
	s_mov_b64 s[12:13], 1
	v_xor_b32_e32 v130, 1, v136
	v_lshlrev_b32_e32 v130, 2, v130
	v_xor_b32_e32 v131, 2, v136
	v_lshlrev_b32_e32 v131, 2, v131
	v_xor_b32_e32 v132, 4, v136
	v_lshlrev_b32_e32 v132, 2, v132
	v_xor_b32_e32 v133, 8, v136
	v_lshlrev_b32_e32 v133, 2, v133
	v_xor_b32_e32 v134, 16, v136
	v_lshlrev_b32_e32 v134, 2, v134
	v_xor_b32_e32 v135, 32, v136
	v_lshlrev_b32_e32 v135, 2, v135
	v_lshlrev_b32_e32 v140, 4, v136
	v_lshlrev_b32_e32 v144, 3, v136
	v_lshlrev_b32_e32 v186, 2, v136
	v_lshlrev_b32_e32 v141, 4, v136
	v_add_u32_e32 v141, 0x400000, v141
	v_lshlrev_b32_e32 v145, 3, v136
	v_add_u32_e32 v145, 0x200000, v145
	v_lshlrev_b32_e32 v187, 2, v136
	v_add_u32_e32 v187, 0x10000, v187
	v_lshlrev_b32_e32 v142, 4, v136
	v_add_u32_e32 v142, 0x800000, v142
	v_lshlrev_b32_e32 v146, 3, v136
	v_add_u32_e32 v146, 0x400000, v146
	v_lshlrev_b32_e32 v188, 2, v136
	v_add_u32_e32 v188, 0x20000, v188
	v_lshlrev_b32_e32 v143, 4, v136
	v_add_u32_e32 v143, 0xc00000, v143
	v_lshlrev_b32_e32 v147, 3, v136
	v_add_u32_e32 v147, 0x600000, v147
	v_lshlrev_b32_e32 v189, 2, v136
	v_add_u32_e32 v189, 0x30000, v189
	s_add_i32 s6, s3, 0x3000
	s_lshl_b32 s6, s6, 12
	s_add_u32 s4, s18, s6
	s_addc_u32 s5, s19, 0
	global_load_dwordx4 v[2:5], v140, s[4:5] nt
	global_load_dwordx4 v[6:9], v140, s[4:5] offset:1024 nt
	global_load_dwordx4 v[10:13], v140, s[4:5] offset:2048 nt
	global_load_dwordx4 v[14:17], v140, s[4:5] offset:3072 nt
	global_load_dwordx4 v[18:21], v141, s[4:5] nt
	global_load_dwordx4 v[22:25], v141, s[4:5] offset:1024 nt
	global_load_dwordx4 v[26:29], v141, s[4:5] offset:2048 nt
	global_load_dwordx4 v[30:33], v141, s[4:5] offset:3072 nt
	global_load_dwordx4 v[34:37], v142, s[4:5] nt
	global_load_dwordx4 v[38:41], v142, s[4:5] offset:1024 nt
	global_load_dwordx4 v[42:45], v142, s[4:5] offset:2048 nt
	global_load_dwordx4 v[46:49], v142, s[4:5] offset:3072 nt
	global_load_dwordx4 v[50:53], v143, s[4:5] nt
	global_load_dwordx4 v[54:57], v143, s[4:5] offset:1024 nt
	global_load_dwordx4 v[58:61], v143, s[4:5] offset:2048 nt
	global_load_dwordx4 v[62:65], v143, s[4:5] offset:3072 nt
	s_add_i32 s6, s3, 0x4000
	s_lshl_b32 s6, s6, 12
	s_add_u32 s4, s18, s6
	s_addc_u32 s5, s19, 0
	global_load_dwordx4 v[66:69], v140, s[4:5] nt
	global_load_dwordx4 v[70:73], v140, s[4:5] offset:1024 nt
	global_load_dwordx4 v[74:77], v140, s[4:5] offset:2048 nt
	global_load_dwordx4 v[78:81], v140, s[4:5] offset:3072 nt
	global_load_dwordx4 v[82:85], v141, s[4:5] nt
	global_load_dwordx4 v[86:89], v141, s[4:5] offset:1024 nt
	global_load_dwordx4 v[90:93], v141, s[4:5] offset:2048 nt
	global_load_dwordx4 v[94:97], v141, s[4:5] offset:3072 nt
	global_load_dwordx4 v[98:101], v142, s[4:5] nt
	global_load_dwordx4 v[102:105], v142, s[4:5] offset:1024 nt
	global_load_dwordx4 v[106:109], v142, s[4:5] offset:2048 nt
	global_load_dwordx4 v[110:113], v142, s[4:5] offset:3072 nt
	global_load_dwordx4 v[114:117], v143, s[4:5] nt
	global_load_dwordx4 v[118:121], v143, s[4:5] offset:1024 nt
	global_load_dwordx4 v[122:125], v143, s[4:5] offset:2048 nt
	global_load_dwordx4 v[126:129], v143, s[4:5] offset:3072 nt
	s_waitcnt vmcnt(16)
	s_add_i32 s6, s3, 0x7000
	s_lshl_b32 s7, s6, 11
	s_add_u32 s10, s40, s7
	s_addc_u32 s11, s41, 0
	s_lshl_b32 s7, s6, 6
	s_add_u32 s6, s40, s7
	s_addc_u32 s7, s41, 0
	s_add_u32 s6, s6, 0x1f800000
	s_addc_u32 s7, s7, 0
	v_mul_f32_e32 v150, v3, v3
	v_mul_f32_e32 v151, v5, v5
	v_fmac_f32_e32 v150, v2, v2
	v_fmac_f32_e32 v151, v4, v4
	v_add_f32_e32 v160, v150, v151
	v_cvt_pk_f16_f32 v170, v2, v3
	v_cvt_pk_f16_f32 v171, v4, v5
	v_mul_f32_e32 v150, v7, v7
	v_mul_f32_e32 v151, v9, v9
	v_fmac_f32_e32 v150, v6, v6
	v_fmac_f32_e32 v151, v8, v8
	v_add_f32_e32 v152, v150, v151
	v_add_f32_e32 v160, v160, v152
	v_cvt_pk_f16_f32 v172, v6, v7
	v_cvt_pk_f16_f32 v173, v8, v9
	v_mul_f32_e32 v150, v11, v11
	v_mul_f32_e32 v151, v13, v13
	v_fmac_f32_e32 v150, v10, v10
	v_fmac_f32_e32 v151, v12, v12
	v_add_f32_e32 v152, v150, v151
	v_add_f32_e32 v160, v160, v152
	v_cvt_pk_f16_f32 v174, v10, v11
	v_cvt_pk_f16_f32 v175, v12, v13
	v_mul_f32_e32 v150, v15, v15
	v_mul_f32_e32 v151, v17, v17
	v_fmac_f32_e32 v150, v14, v14
	v_fmac_f32_e32 v151, v16, v16
	v_add_f32_e32 v152, v150, v151
	v_add_f32_e32 v160, v160, v152
	v_cvt_pk_f16_f32 v176, v14, v15
	v_cvt_pk_f16_f32 v177, v16, v17
	global_store_dwordx2 v144, v[170:171], s[10:11]
	global_store_dwordx2 v144, v[172:173], s[10:11] offset:512
	global_store_dwordx2 v144, v[174:175], s[10:11] offset:1024
	global_store_dwordx2 v144, v[176:177], s[10:11] offset:1536
	v_mul_f32_e32 v150, v19, v19
	v_mul_f32_e32 v151, v21, v21
	v_fmac_f32_e32 v150, v18, v18
	v_fmac_f32_e32 v151, v20, v20
	v_add_f32_e32 v161, v150, v151
	v_cvt_pk_f16_f32 v178, v18, v19
	v_cvt_pk_f16_f32 v179, v20, v21
	v_mul_f32_e32 v150, v23, v23
	v_mul_f32_e32 v151, v25, v25
	v_fmac_f32_e32 v150, v22, v22
	v_fmac_f32_e32 v151, v24, v24
	v_add_f32_e32 v152, v150, v151
	v_add_f32_e32 v161, v161, v152
	v_cvt_pk_f16_f32 v180, v22, v23
	v_cvt_pk_f16_f32 v181, v24, v25
	v_mul_f32_e32 v150, v27, v27
	v_mul_f32_e32 v151, v29, v29
	v_fmac_f32_e32 v150, v26, v26
	v_fmac_f32_e32 v151, v28, v28
	v_add_f32_e32 v152, v150, v151
	v_add_f32_e32 v161, v161, v152
	v_cvt_pk_f16_f32 v182, v26, v27
	v_cvt_pk_f16_f32 v183, v28, v29
	v_mul_f32_e32 v150, v31, v31
	v_mul_f32_e32 v151, v33, v33
	v_fmac_f32_e32 v150, v30, v30
	v_fmac_f32_e32 v151, v32, v32
	v_add_f32_e32 v152, v150, v151
	v_add_f32_e32 v161, v161, v152
; __device__ void p0_xconv(const Args& a) {
;     ...
;                 float ss = 0.f;
; #pragma unroll
;                 for (int i = 0; i < 4; ++i) {
;                     const f32x4 x = v[r][i];
;                     ss += (x[0] * x[0] + x[1] * x[1]) + (x[2] * x[2] + x[3] * x[3]);
;                     f16x4 h; h[0] = (f16)x[0]; h[1] = (f16)x[1]; h[2] = (f16)x[2]; h[3] = (f16)x[3];
;                     *(f16x4*)(XH + (size_t)row * DM + i * 256 + lane * 4) = h;
;                 }
; #pragma unroll
;                 for (int o = 1; o < 64; o <<= 1) ss += __shfl_xor(ss, o);
;                 if (lane < 16) SS[(size_t)row * 16 + lane] = (lane == 0) ? ss : 0.f;
;             }
;         }
;     }
; }
	v_cvt_pk_f16_f32 v184, v30, v31
	v_cvt_pk_f16_f32 v185, v32, v33
	global_store_dwordx2 v145, v[178:179], s[10:11]
	global_store_dwordx2 v145, v[180:181], s[10:11] offset:512
	global_store_dwordx2 v145, v[182:183], s[10:11] offset:1024
	global_store_dwordx2 v145, v[184:185], s[10:11] offset:1536
	v_mul_f32_e32 v150, v35, v35
	v_mul_f32_e32 v151, v37, v37
	v_fmac_f32_e32 v150, v34, v34
	v_fmac_f32_e32 v151, v36, v36
	v_add_f32_e32 v162, v150, v151
	v_cvt_pk_f16_f32 v170, v34, v35
	v_cvt_pk_f16_f32 v171, v36, v37
	v_mul_f32_e32 v150, v39, v39
	v_mul_f32_e32 v151, v41, v41
	v_fmac_f32_e32 v150, v38, v38
	v_fmac_f32_e32 v151, v40, v40
	v_add_f32_e32 v152, v150, v151
	v_add_f32_e32 v162, v162, v152
	v_cvt_pk_f16_f32 v172, v38, v39
	v_cvt_pk_f16_f32 v173, v40, v41
	v_mul_f32_e32 v150, v43, v43
	v_mul_f32_e32 v151, v45, v45
	v_fmac_f32_e32 v150, v42, v42
	v_fmac_f32_e32 v151, v44, v44
	v_add_f32_e32 v152, v150, v151
	v_add_f32_e32 v162, v162, v152
	v_cvt_pk_f16_f32 v174, v42, v43
	v_cvt_pk_f16_f32 v175, v44, v45
	v_mul_f32_e32 v150, v47, v47
	v_mul_f32_e32 v151, v49, v49
	v_fmac_f32_e32 v150, v46, v46
	v_fmac_f32_e32 v151, v48, v48
	v_add_f32_e32 v152, v150, v151
	v_add_f32_e32 v162, v162, v152
	v_cvt_pk_f16_f32 v176, v46, v47
	v_cvt_pk_f16_f32 v177, v48, v49
	global_store_dwordx2 v146, v[170:171], s[10:11]
	global_store_dwordx2 v146, v[172:173], s[10:11] offset:512
	global_store_dwordx2 v146, v[174:175], s[10:11] offset:1024
	global_store_dwordx2 v146, v[176:177], s[10:11] offset:1536
	v_mul_f32_e32 v150, v51, v51
	v_mul_f32_e32 v151, v53, v53
	v_fmac_f32_e32 v150, v50, v50
	v_fmac_f32_e32 v151, v52, v52
	v_add_f32_e32 v163, v150, v151
	v_cvt_pk_f16_f32 v178, v50, v51
	v_cvt_pk_f16_f32 v179, v52, v53
	v_mul_f32_e32 v150, v55, v55
	v_mul_f32_e32 v151, v57, v57
	v_fmac_f32_e32 v150, v54, v54
	v_fmac_f32_e32 v151, v56, v56
	v_add_f32_e32 v152, v150, v151
	v_add_f32_e32 v163, v163, v152
	v_cvt_pk_f16_f32 v180, v54, v55
	v_cvt_pk_f16_f32 v181, v56, v57
	v_mul_f32_e32 v150, v59, v59
	v_mul_f32_e32 v151, v61, v61
	v_fmac_f32_e32 v150, v58, v58
	v_fmac_f32_e32 v151, v60, v60
	v_add_f32_e32 v152, v150, v151
	v_add_f32_e32 v163, v163, v152
	v_cvt_pk_f16_f32 v182, v58, v59
	v_cvt_pk_f16_f32 v183, v60, v61
	v_mul_f32_e32 v150, v63, v63
	v_mul_f32_e32 v151, v65, v65
	v_fmac_f32_e32 v150, v62, v62
	v_fmac_f32_e32 v151, v64, v64
	v_add_f32_e32 v152, v150, v151
	v_add_f32_e32 v163, v163, v152
	v_cvt_pk_f16_f32 v184, v62, v63
	v_cvt_pk_f16_f32 v185, v64, v65
	global_store_dwordx2 v147, v[178:179], s[10:11]
	global_store_dwordx2 v147, v[180:181], s[10:11] offset:512
	global_store_dwordx2 v147, v[182:183], s[10:11] offset:1024
	global_store_dwordx2 v147, v[184:185], s[10:11] offset:1536
	ds_bpermute_b32 v164, v130, v160
	ds_bpermute_b32 v165, v130, v161
	ds_bpermute_b32 v166, v130, v162
	ds_bpermute_b32 v167, v130, v163
	s_waitcnt lgkmcnt(0)
	v_add_f32_e32 v160, v160, v164
	v_add_f32_e32 v161, v161, v165
	v_add_f32_e32 v162, v162, v166
	v_add_f32_e32 v163, v163, v167
	ds_bpermute_b32 v164, v131, v160
	ds_bpermute_b32 v165, v131, v161
	ds_bpermute_b32 v166, v131, v162
	ds_bpermute_b32 v167, v131, v163
	s_waitcnt lgkmcnt(0)
	v_add_f32_e32 v160, v160, v164
	v_add_f32_e32 v161, v161, v165
	v_add_f32_e32 v162, v162, v166
	v_add_f32_e32 v163, v163, v167
	ds_bpermute_b32 v164, v132, v160
	ds_bpermute_b32 v165, v132, v161
	ds_bpermute_b32 v166, v132, v162
	ds_bpermute_b32 v167, v132, v163
	s_waitcnt lgkmcnt(0)
	v_add_f32_e32 v160, v160, v164
	v_add_f32_e32 v161, v161, v165
	v_add_f32_e32 v162, v162, v166
	v_add_f32_e32 v163, v163, v167
	ds_bpermute_b32 v164, v133, v160
	ds_bpermute_b32 v165, v133, v161
	ds_bpermute_b32 v166, v133, v162
	ds_bpermute_b32 v167, v133, v163
	s_waitcnt lgkmcnt(0)
	v_add_f32_e32 v160, v160, v164
	v_add_f32_e32 v161, v161, v165
	v_add_f32_e32 v162, v162, v166
	v_add_f32_e32 v163, v163, v167
	ds_bpermute_b32 v164, v134, v160
	ds_bpermute_b32 v165, v134, v161
	ds_bpermute_b32 v166, v134, v162
	ds_bpermute_b32 v167, v134, v163
	s_waitcnt lgkmcnt(0)
	v_add_f32_e32 v160, v160, v164
	v_add_f32_e32 v161, v161, v165
	v_add_f32_e32 v162, v162, v166
	v_add_f32_e32 v163, v163, v167
	ds_bpermute_b32 v164, v135, v160
	ds_bpermute_b32 v165, v135, v161
	ds_bpermute_b32 v166, v135, v162
	ds_bpermute_b32 v167, v135, v163
	s_waitcnt lgkmcnt(0)
	v_add_f32_e32 v160, v160, v164
	v_add_f32_e32 v161, v161, v165
	v_add_f32_e32 v162, v162, v166
	v_add_f32_e32 v163, v163, v167
	v_cndmask_b32_e64 v164, 0, v160, s[12:13]
	v_cndmask_b32_e64 v165, 0, v161, s[12:13]
	v_cndmask_b32_e64 v166, 0, v162, s[12:13]
	v_cndmask_b32_e64 v167, 0, v163, s[12:13]
	s_mov_b64 exec, 0xffff
	global_store_dword v186, v164, s[6:7]
	global_store_dword v187, v165, s[6:7]
	global_store_dword v188, v166, s[6:7]
	global_store_dword v189, v167, s[6:7]
	s_mov_b64 exec, -1
	s_barrier
; __device__ void p0_xconv(const Args& a) {
;     ...
;         for (int r = 0; r < 4; ++r) {
;             const int row = row0 + r * nwv;
;             if (row < MROWS) {
;                 const float* src = (row < ROWS_PROMPT) ? a.x_prompt + (size_t)row * DM : a.x_sample + (size_t)(row - ROWS_PROMPT) * DM;
; #pragma unroll
;                 for (int i = 0; i < 4; ++i) v[r][i] = __builtin_nontemporal_load((const f32x4*)(src + i * 256 + lane * 4));
;             }
;         }
; #pragma unroll
;         for (int r = 0; r < 4; ++r) {
;             const int row = row0 + r * nwv;
;             if (row < MROWS) {
;                 float ss = 0.f;
; #pragma unroll
;                 for (int i = 0; i < 4; ++i) {
;                     const f32x4 x = v[r][i];
;                     ss += (x[0] * x[0] + x[1] * x[1]) + (x[2] * x[2] + x[3] * x[3]);
;                     f16x4 h; h[0] = (f16)x[0]; h[1] = (f16)x[1]; h[2] = (f16)x[2]; h[3] = (f16)x[3];
;                     *(f16x4*)(XH + (size_t)row * DM + i * 256 + lane * 4) = h;
;                 }
	s_add_i32 s6, s3, 0x5000
	s_lshl_b32 s6, s6, 12
	s_add_u32 s4, s18, s6
	s_addc_u32 s5, s19, 0
	global_load_dwordx4 v[2:5], v140, s[4:5] nt
	global_load_dwordx4 v[6:9], v140, s[4:5] offset:1024 nt
	global_load_dwordx4 v[10:13], v140, s[4:5] offset:2048 nt
	global_load_dwordx4 v[14:17], v140, s[4:5] offset:3072 nt
	global_load_dwordx4 v[18:21], v141, s[4:5] nt
	global_load_dwordx4 v[22:25], v141, s[4:5] offset:1024 nt
	global_load_dwordx4 v[26:29], v141, s[4:5] offset:2048 nt
	global_load_dwordx4 v[30:33], v141, s[4:5] offset:3072 nt
	global_load_dwordx4 v[34:37], v142, s[4:5] nt
	global_load_dwordx4 v[38:41], v142, s[4:5] offset:1024 nt
	global_load_dwordx4 v[42:45], v142, s[4:5] offset:2048 nt
	global_load_dwordx4 v[46:49], v142, s[4:5] offset:3072 nt
	global_load_dwordx4 v[50:53], v143, s[4:5] nt
	global_load_dwordx4 v[54:57], v143, s[4:5] offset:1024 nt
	global_load_dwordx4 v[58:61], v143, s[4:5] offset:2048 nt
	global_load_dwordx4 v[62:65], v143, s[4:5] offset:3072 nt
	s_waitcnt vmcnt(36)
	s_add_i32 s6, s3, 0x8000
	s_lshl_b32 s7, s6, 11
	s_add_u32 s10, s40, s7
	s_addc_u32 s11, s41, 0
	s_lshl_b32 s7, s6, 6
	s_add_u32 s6, s40, s7
	s_addc_u32 s7, s41, 0
	s_add_u32 s6, s6, 0x1f800000
	s_addc_u32 s7, s7, 0
	v_mul_f32_e32 v150, v67, v67
	v_mul_f32_e32 v151, v69, v69
	v_fmac_f32_e32 v150, v66, v66
	v_fmac_f32_e32 v151, v68, v68
	v_add_f32_e32 v160, v150, v151
	v_cvt_pk_f16_f32 v170, v66, v67
	v_cvt_pk_f16_f32 v171, v68, v69
	v_mul_f32_e32 v150, v71, v71
	v_mul_f32_e32 v151, v73, v73
	v_fmac_f32_e32 v150, v70, v70
	v_fmac_f32_e32 v151, v72, v72
	v_add_f32_e32 v152, v150, v151
	v_add_f32_e32 v160, v160, v152
	v_cvt_pk_f16_f32 v172, v70, v71
	v_cvt_pk_f16_f32 v173, v72, v73
	v_mul_f32_e32 v150, v75, v75
	v_mul_f32_e32 v151, v77, v77
	v_fmac_f32_e32 v150, v74, v74
	v_fmac_f32_e32 v151, v76, v76
	v_add_f32_e32 v152, v150, v151
	v_add_f32_e32 v160, v160, v152
	v_cvt_pk_f16_f32 v174, v74, v75
	v_cvt_pk_f16_f32 v175, v76, v77
	v_mul_f32_e32 v150, v79, v79
	v_mul_f32_e32 v151, v81, v81
	v_fmac_f32_e32 v150, v78, v78
	v_fmac_f32_e32 v151, v80, v80
	v_add_f32_e32 v152, v150, v151
	v_add_f32_e32 v160, v160, v152
	v_cvt_pk_f16_f32 v176, v78, v79
	v_cvt_pk_f16_f32 v177, v80, v81
	global_store_dwordx2 v144, v[170:171], s[10:11]
	global_store_dwordx2 v144, v[172:173], s[10:11] offset:512
	global_store_dwordx2 v144, v[174:175], s[10:11] offset:1024
	global_store_dwordx2 v144, v[176:177], s[10:11] offset:1536
	v_mul_f32_e32 v150, v83, v83
	v_mul_f32_e32 v151, v85, v85
	v_fmac_f32_e32 v150, v82, v82
	v_fmac_f32_e32 v151, v84, v84
	v_add_f32_e32 v161, v150, v151
	v_cvt_pk_f16_f32 v178, v82, v83
	v_cvt_pk_f16_f32 v179, v84, v85
	v_mul_f32_e32 v150, v87, v87
	v_mul_f32_e32 v151, v89, v89
	v_fmac_f32_e32 v150, v86, v86
	v_fmac_f32_e32 v151, v88, v88
	v_add_f32_e32 v152, v150, v151
	v_add_f32_e32 v161, v161, v152
	v_cvt_pk_f16_f32 v180, v86, v87
	v_cvt_pk_f16_f32 v181, v88, v89
	v_mul_f32_e32 v150, v91, v91
	v_mul_f32_e32 v151, v93, v93
	v_fmac_f32_e32 v150, v90, v90
	v_fmac_f32_e32 v151, v92, v92
	v_add_f32_e32 v152, v150, v151
	v_add_f32_e32 v161, v161, v152
	v_cvt_pk_f16_f32 v182, v90, v91
	v_cvt_pk_f16_f32 v183, v92, v93
	v_mul_f32_e32 v150, v95, v95
	v_mul_f32_e32 v151, v97, v97
	v_fmac_f32_e32 v150, v94, v94
	v_fmac_f32_e32 v151, v96, v96
	v_add_f32_e32 v152, v150, v151
	v_add_f32_e32 v161, v161, v152
	v_cvt_pk_f16_f32 v184, v94, v95
	v_cvt_pk_f16_f32 v185, v96, v97
	global_store_dwordx2 v145, v[178:179], s[10:11]
	global_store_dwordx2 v145, v[180:181], s[10:11] offset:512
	global_store_dwordx2 v145, v[182:183], s[10:11] offset:1024
	global_store_dwordx2 v145, v[184:185], s[10:11] offset:1536
	v_mul_f32_e32 v150, v99, v99
	v_mul_f32_e32 v151, v101, v101
	v_fmac_f32_e32 v150, v98, v98
	v_fmac_f32_e32 v151, v100, v100
	v_add_f32_e32 v162, v150, v151
	v_cvt_pk_f16_f32 v170, v98, v99
	v_cvt_pk_f16_f32 v171, v100, v101
	v_mul_f32_e32 v150, v103, v103
	v_mul_f32_e32 v151, v105, v105
	v_fmac_f32_e32 v150, v102, v102
	v_fmac_f32_e32 v151, v104, v104
	v_add_f32_e32 v152, v150, v151
	v_add_f32_e32 v162, v162, v152
	v_cvt_pk_f16_f32 v172, v102, v103
	v_cvt_pk_f16_f32 v173, v104, v105
	v_mul_f32_e32 v150, v107, v107
	v_mul_f32_e32 v151, v109, v109
	v_fmac_f32_e32 v150, v106, v106
	v_fmac_f32_e32 v151, v108, v108
	v_add_f32_e32 v152, v150, v151
	v_add_f32_e32 v162, v162, v152
	v_cvt_pk_f16_f32 v174, v106, v107
	v_cvt_pk_f16_f32 v175, v108, v109
	v_mul_f32_e32 v150, v111, v111
	v_mul_f32_e32 v151, v113, v113
	v_fmac_f32_e32 v150, v110, v110
	v_fmac_f32_e32 v151, v112, v112
	v_add_f32_e32 v152, v150, v151
	v_add_f32_e32 v162, v162, v152
	v_cvt_pk_f16_f32 v176, v110, v111
	v_cvt_pk_f16_f32 v177, v112, v113
	global_store_dwordx2 v146, v[170:171], s[10:11]
	global_store_dwordx2 v146, v[172:173], s[10:11] offset:512
	global_store_dwordx2 v146, v[174:175], s[10:11] offset:1024
	global_store_dwordx2 v146, v[176:177], s[10:11] offset:1536
	v_mul_f32_e32 v150, v115, v115
	v_mul_f32_e32 v151, v117, v117
	v_fmac_f32_e32 v150, v114, v114
	v_fmac_f32_e32 v151, v116, v116
	v_add_f32_e32 v163, v150, v151
	v_cvt_pk_f16_f32 v178, v114, v115
	v_cvt_pk_f16_f32 v179, v116, v117
	v_mul_f32_e32 v150, v119, v119
	v_mul_f32_e32 v151, v121, v121
	v_fmac_f32_e32 v150, v118, v118
	v_fmac_f32_e32 v151, v120, v120
	v_add_f32_e32 v152, v150, v151
	v_add_f32_e32 v163, v163, v152
	v_cvt_pk_f16_f32 v180, v118, v119
	v_cvt_pk_f16_f32 v181, v120, v121
	v_mul_f32_e32 v150, v123, v123
	v_mul_f32_e32 v151, v125, v125
	v_fmac_f32_e32 v150, v122, v122
	v_fmac_f32_e32 v151, v124, v124
	v_add_f32_e32 v152, v150, v151
	v_add_f32_e32 v163, v163, v152
	v_cvt_pk_f16_f32 v182, v122, v123
	v_cvt_pk_f16_f32 v183, v124, v125
	v_mul_f32_e32 v150, v127, v127
	v_mul_f32_e32 v151, v129, v129
	v_fmac_f32_e32 v150, v126, v126
	v_fmac_f32_e32 v151, v128, v128
	v_add_f32_e32 v152, v150, v151
	v_add_f32_e32 v163, v163, v152
	v_cvt_pk_f16_f32 v184, v126, v127
	v_cvt_pk_f16_f32 v185, v128, v129
	global_store_dwordx2 v147, v[178:179], s[10:11]
	global_store_dwordx2 v147, v[180:181], s[10:11] offset:512
	global_store_dwordx2 v147, v[182:183], s[10:11] offset:1024
	global_store_dwordx2 v147, v[184:185], s[10:11] offset:1536
	ds_bpermute_b32 v164, v130, v160
	ds_bpermute_b32 v165, v130, v161
	ds_bpermute_b32 v166, v130, v162
	ds_bpermute_b32 v167, v130, v163
	s_waitcnt lgkmcnt(0)
; __device__ void p0_xconv(const Args& a) {
;     ...
; #pragma unroll
;         for (int r = 0; r < 4; ++r) {
;             const int row = row0 + r * nwv;
;             if (row < MROWS) {
;                 float ss = 0.f;
; #pragma unroll
;                 for (int i = 0; i < 4; ++i) {
;                     const f32x4 x = v[r][i];
;                     ss += (x[0] * x[0] + x[1] * x[1]) + (x[2] * x[2] + x[3] * x[3]);
;                     f16x4 h; h[0] = (f16)x[0]; h[1] = (f16)x[1]; h[2] = (f16)x[2]; h[3] = (f16)x[3];
;                     *(f16x4*)(XH + (size_t)row * DM + i * 256 + lane * 4) = h;
;                 }
;     ...
;                 for (int o = 1; o < 64; o <<= 1) ss += __shfl_xor(ss, o);
;                 if (lane < 16) SS[(size_t)row * 16 + lane] = (lane == 0) ? ss : 0.f;
	v_add_f32_e32 v160, v160, v164
	v_add_f32_e32 v161, v161, v165
	v_add_f32_e32 v162, v162, v166
	v_add_f32_e32 v163, v163, v167
	ds_bpermute_b32 v164, v131, v160
	ds_bpermute_b32 v165, v131, v161
	ds_bpermute_b32 v166, v131, v162
	ds_bpermute_b32 v167, v131, v163
	s_waitcnt lgkmcnt(0)
	v_add_f32_e32 v160, v160, v164
	v_add_f32_e32 v161, v161, v165
	v_add_f32_e32 v162, v162, v166
	v_add_f32_e32 v163, v163, v167
	ds_bpermute_b32 v164, v132, v160
	ds_bpermute_b32 v165, v132, v161
	ds_bpermute_b32 v166, v132, v162
	ds_bpermute_b32 v167, v132, v163
	s_waitcnt lgkmcnt(0)
	v_add_f32_e32 v160, v160, v164
	v_add_f32_e32 v161, v161, v165
	v_add_f32_e32 v162, v162, v166
	v_add_f32_e32 v163, v163, v167
	ds_bpermute_b32 v164, v133, v160
	ds_bpermute_b32 v165, v133, v161
	ds_bpermute_b32 v166, v133, v162
	ds_bpermute_b32 v167, v133, v163
	s_waitcnt lgkmcnt(0)
	v_add_f32_e32 v160, v160, v164
	v_add_f32_e32 v161, v161, v165
	v_add_f32_e32 v162, v162, v166
	v_add_f32_e32 v163, v163, v167
	ds_bpermute_b32 v164, v134, v160
	ds_bpermute_b32 v165, v134, v161
	ds_bpermute_b32 v166, v134, v162
	ds_bpermute_b32 v167, v134, v163
	s_waitcnt lgkmcnt(0)
	v_add_f32_e32 v160, v160, v164
	v_add_f32_e32 v161, v161, v165
	v_add_f32_e32 v162, v162, v166
	v_add_f32_e32 v163, v163, v167
	ds_bpermute_b32 v164, v135, v160
	ds_bpermute_b32 v165, v135, v161
	ds_bpermute_b32 v166, v135, v162
	ds_bpermute_b32 v167, v135, v163
	s_waitcnt lgkmcnt(0)
	v_add_f32_e32 v160, v160, v164
	v_add_f32_e32 v161, v161, v165
	v_add_f32_e32 v162, v162, v166
	v_add_f32_e32 v163, v163, v167
	v_cndmask_b32_e64 v164, 0, v160, s[12:13]
	v_cndmask_b32_e64 v165, 0, v161, s[12:13]
	v_cndmask_b32_e64 v166, 0, v162, s[12:13]
	v_cndmask_b32_e64 v167, 0, v163, s[12:13]
	s_mov_b64 exec, 0xffff
	global_store_dword v186, v164, s[6:7]
	global_store_dword v187, v165, s[6:7]
	global_store_dword v188, v166, s[6:7]
	global_store_dword v189, v167, s[6:7]
	s_mov_b64 exec, -1
	s_add_i32 s6, s3, 0x6000
	s_lshl_b32 s6, s6, 12
	s_add_u32 s4, s18, s6
	s_addc_u32 s5, s19, 0
	global_load_dwordx4 v[66:69], v140, s[4:5] nt
	global_load_dwordx4 v[70:73], v140, s[4:5] offset:1024 nt
	global_load_dwordx4 v[74:77], v140, s[4:5] offset:2048 nt
	global_load_dwordx4 v[78:81], v140, s[4:5] offset:3072 nt
	global_load_dwordx4 v[82:85], v141, s[4:5] nt
	global_load_dwordx4 v[86:89], v141, s[4:5] offset:1024 nt
	global_load_dwordx4 v[90:93], v141, s[4:5] offset:2048 nt
	global_load_dwordx4 v[94:97], v141, s[4:5] offset:3072 nt
	global_load_dwordx4 v[98:101], v142, s[4:5] nt
	global_load_dwordx4 v[102:105], v142, s[4:5] offset:1024 nt
	global_load_dwordx4 v[106:109], v142, s[4:5] offset:2048 nt
	global_load_dwordx4 v[110:113], v142, s[4:5] offset:3072 nt
	global_load_dwordx4 v[114:117], v143, s[4:5] nt
	global_load_dwordx4 v[118:121], v143, s[4:5] offset:1024 nt
	global_load_dwordx4 v[122:125], v143, s[4:5] offset:2048 nt
	global_load_dwordx4 v[126:129], v143, s[4:5] offset:3072 nt
	s_waitcnt vmcnt(36)
	s_add_i32 s6, s3, 0x9000
	s_lshl_b32 s7, s6, 11
	s_add_u32 s10, s40, s7
	s_addc_u32 s11, s41, 0
	s_lshl_b32 s7, s6, 6
	s_add_u32 s6, s40, s7
	s_addc_u32 s7, s41, 0
	s_add_u32 s6, s6, 0x1f800000
	s_addc_u32 s7, s7, 0
	v_mul_f32_e32 v150, v3, v3
	v_mul_f32_e32 v151, v5, v5
	v_fmac_f32_e32 v150, v2, v2
	v_fmac_f32_e32 v151, v4, v4
	v_add_f32_e32 v160, v150, v151
	v_cvt_pk_f16_f32 v170, v2, v3
	v_cvt_pk_f16_f32 v171, v4, v5
	v_mul_f32_e32 v150, v7, v7
	v_mul_f32_e32 v151, v9, v9
	v_fmac_f32_e32 v150, v6, v6
	v_fmac_f32_e32 v151, v8, v8
	v_add_f32_e32 v152, v150, v151
	v_add_f32_e32 v160, v160, v152
	v_cvt_pk_f16_f32 v172, v6, v7
	v_cvt_pk_f16_f32 v173, v8, v9
	v_mul_f32_e32 v150, v11, v11
	v_mul_f32_e32 v151, v13, v13
	v_fmac_f32_e32 v150, v10, v10
	v_fmac_f32_e32 v151, v12, v12
	v_add_f32_e32 v152, v150, v151
	v_add_f32_e32 v160, v160, v152
	v_cvt_pk_f16_f32 v174, v10, v11
	v_cvt_pk_f16_f32 v175, v12, v13
	v_mul_f32_e32 v150, v15, v15
	v_mul_f32_e32 v151, v17, v17
	v_fmac_f32_e32 v150, v14, v14
	v_fmac_f32_e32 v151, v16, v16
	v_add_f32_e32 v152, v150, v151
	v_add_f32_e32 v160, v160, v152
	v_cvt_pk_f16_f32 v176, v14, v15
	v_cvt_pk_f16_f32 v177, v16, v17
	global_store_dwordx2 v144, v[170:171], s[10:11]
	global_store_dwordx2 v144, v[172:173], s[10:11] offset:512
	global_store_dwordx2 v144, v[174:175], s[10:11] offset:1024
	global_store_dwordx2 v144, v[176:177], s[10:11] offset:1536
	v_mul_f32_e32 v150, v19, v19
	v_mul_f32_e32 v151, v21, v21
	v_fmac_f32_e32 v150, v18, v18
	v_fmac_f32_e32 v151, v20, v20
	v_add_f32_e32 v161, v150, v151
	v_cvt_pk_f16_f32 v178, v18, v19
	v_cvt_pk_f16_f32 v179, v20, v21
	v_mul_f32_e32 v150, v23, v23
	v_mul_f32_e32 v151, v25, v25
	v_fmac_f32_e32 v150, v22, v22
	v_fmac_f32_e32 v151, v24, v24
	v_add_f32_e32 v152, v150, v151
	v_add_f32_e32 v161, v161, v152
	v_cvt_pk_f16_f32 v180, v22, v23
	v_cvt_pk_f16_f32 v181, v24, v25
	v_mul_f32_e32 v150, v27, v27
	v_mul_f32_e32 v151, v29, v29
	v_fmac_f32_e32 v150, v26, v26
	v_fmac_f32_e32 v151, v28, v28
	v_add_f32_e32 v152, v150, v151
	v_add_f32_e32 v161, v161, v152
	v_cvt_pk_f16_f32 v182, v26, v27
	v_cvt_pk_f16_f32 v183, v28, v29
	v_mul_f32_e32 v150, v31, v31
	v_mul_f32_e32 v151, v33, v33
	v_fmac_f32_e32 v150, v30, v30
	v_fmac_f32_e32 v151, v32, v32
	v_add_f32_e32 v152, v150, v151
	v_add_f32_e32 v161, v161, v152
	v_cvt_pk_f16_f32 v184, v30, v31
	v_cvt_pk_f16_f32 v185, v32, v33
	global_store_dwordx2 v145, v[178:179], s[10:11]
	global_store_dwordx2 v145, v[180:181], s[10:11] offset:512
	global_store_dwordx2 v145, v[182:183], s[10:11] offset:1024
	global_store_dwordx2 v145, v[184:185], s[10:11] offset:1536
	v_mul_f32_e32 v150, v35, v35
	v_mul_f32_e32 v151, v37, v37
	v_fmac_f32_e32 v150, v34, v34
; __device__ void p0_xconv(const Args& a) {
;     ...
;         for (int r = 0; r < 4; ++r) {
;             const int row = row0 + r * nwv;
;             if (row < MROWS) {
;                 const float* src = (row < ROWS_PROMPT) ? a.x_prompt + (size_t)row * DM : a.x_sample + (size_t)(row - ROWS_PROMPT) * DM;
; #pragma unroll
;                 for (int i = 0; i < 4; ++i) v[r][i] = __builtin_nontemporal_load((const f32x4*)(src + i * 256 + lane * 4));
;             }
;     ...
; #pragma unroll
;         for (int r = 0; r < 4; ++r) {
;             const int row = row0 + r * nwv;
;             if (row < MROWS) {
;                 float ss = 0.f;
; #pragma unroll
;                 for (int i = 0; i < 4; ++i) {
;                     const f32x4 x = v[r][i];
;                     ss += (x[0] * x[0] + x[1] * x[1]) + (x[2] * x[2] + x[3] * x[3]);
;                     f16x4 h; h[0] = (f16)x[0]; h[1] = (f16)x[1]; h[2] = (f16)x[2]; h[3] = (f16)x[3];
;                     *(f16x4*)(XH + (size_t)row * DM + i * 256 + lane * 4) = h;
;                 }
; #pragma unroll
;                 for (int o = 1; o < 64; o <<= 1) ss += __shfl_xor(ss, o);
;                 if (lane < 16) SS[(size_t)row * 16 + lane] = (lane == 0) ? ss : 0.f;
	v_fmac_f32_e32 v151, v36, v36
	v_add_f32_e32 v162, v150, v151
	v_cvt_pk_f16_f32 v170, v34, v35
	v_cvt_pk_f16_f32 v171, v36, v37
	v_mul_f32_e32 v150, v39, v39
	v_mul_f32_e32 v151, v41, v41
	v_fmac_f32_e32 v150, v38, v38
	v_fmac_f32_e32 v151, v40, v40
	v_add_f32_e32 v152, v150, v151
	v_add_f32_e32 v162, v162, v152
	v_cvt_pk_f16_f32 v172, v38, v39
	v_cvt_pk_f16_f32 v173, v40, v41
	v_mul_f32_e32 v150, v43, v43
	v_mul_f32_e32 v151, v45, v45
	v_fmac_f32_e32 v150, v42, v42
	v_fmac_f32_e32 v151, v44, v44
	v_add_f32_e32 v152, v150, v151
	v_add_f32_e32 v162, v162, v152
	v_cvt_pk_f16_f32 v174, v42, v43
	v_cvt_pk_f16_f32 v175, v44, v45
	v_mul_f32_e32 v150, v47, v47
	v_mul_f32_e32 v151, v49, v49
	v_fmac_f32_e32 v150, v46, v46
	v_fmac_f32_e32 v151, v48, v48
	v_add_f32_e32 v152, v150, v151
	v_add_f32_e32 v162, v162, v152
	v_cvt_pk_f16_f32 v176, v46, v47
	v_cvt_pk_f16_f32 v177, v48, v49
	global_store_dwordx2 v146, v[170:171], s[10:11]
	global_store_dwordx2 v146, v[172:173], s[10:11] offset:512
	global_store_dwordx2 v146, v[174:175], s[10:11] offset:1024
	global_store_dwordx2 v146, v[176:177], s[10:11] offset:1536
	v_mul_f32_e32 v150, v51, v51
	v_mul_f32_e32 v151, v53, v53
	v_fmac_f32_e32 v150, v50, v50
	v_fmac_f32_e32 v151, v52, v52
	v_add_f32_e32 v163, v150, v151
	v_cvt_pk_f16_f32 v178, v50, v51
	v_cvt_pk_f16_f32 v179, v52, v53
	v_mul_f32_e32 v150, v55, v55
	v_mul_f32_e32 v151, v57, v57
	v_fmac_f32_e32 v150, v54, v54
	v_fmac_f32_e32 v151, v56, v56
	v_add_f32_e32 v152, v150, v151
	v_add_f32_e32 v163, v163, v152
	v_cvt_pk_f16_f32 v180, v54, v55
	v_cvt_pk_f16_f32 v181, v56, v57
	v_mul_f32_e32 v150, v59, v59
	v_mul_f32_e32 v151, v61, v61
	v_fmac_f32_e32 v150, v58, v58
	v_fmac_f32_e32 v151, v60, v60
	v_add_f32_e32 v152, v150, v151
	v_add_f32_e32 v163, v163, v152
	v_cvt_pk_f16_f32 v182, v58, v59
	v_cvt_pk_f16_f32 v183, v60, v61
	v_mul_f32_e32 v150, v63, v63
	v_mul_f32_e32 v151, v65, v65
	v_fmac_f32_e32 v150, v62, v62
	v_fmac_f32_e32 v151, v64, v64
	v_add_f32_e32 v152, v150, v151
	v_add_f32_e32 v163, v163, v152
	v_cvt_pk_f16_f32 v184, v62, v63
	v_cvt_pk_f16_f32 v185, v64, v65
	global_store_dwordx2 v147, v[178:179], s[10:11]
	global_store_dwordx2 v147, v[180:181], s[10:11] offset:512
	global_store_dwordx2 v147, v[182:183], s[10:11] offset:1024
	global_store_dwordx2 v147, v[184:185], s[10:11] offset:1536
	ds_bpermute_b32 v164, v130, v160
	ds_bpermute_b32 v165, v130, v161
	ds_bpermute_b32 v166, v130, v162
	ds_bpermute_b32 v167, v130, v163
	s_waitcnt lgkmcnt(0)
	v_add_f32_e32 v160, v160, v164
	v_add_f32_e32 v161, v161, v165
	v_add_f32_e32 v162, v162, v166
	v_add_f32_e32 v163, v163, v167
	ds_bpermute_b32 v164, v131, v160
	ds_bpermute_b32 v165, v131, v161
	ds_bpermute_b32 v166, v131, v162
	ds_bpermute_b32 v167, v131, v163
	s_waitcnt lgkmcnt(0)
	v_add_f32_e32 v160, v160, v164
	v_add_f32_e32 v161, v161, v165
	v_add_f32_e32 v162, v162, v166
	v_add_f32_e32 v163, v163, v167
	ds_bpermute_b32 v164, v132, v160
	ds_bpermute_b32 v165, v132, v161
	ds_bpermute_b32 v166, v132, v162
	ds_bpermute_b32 v167, v132, v163
	s_waitcnt lgkmcnt(0)
	v_add_f32_e32 v160, v160, v164
	v_add_f32_e32 v161, v161, v165
	v_add_f32_e32 v162, v162, v166
	v_add_f32_e32 v163, v163, v167
	ds_bpermute_b32 v164, v133, v160
	ds_bpermute_b32 v165, v133, v161
	ds_bpermute_b32 v166, v133, v162
	ds_bpermute_b32 v167, v133, v163
	s_waitcnt lgkmcnt(0)
	v_add_f32_e32 v160, v160, v164
	v_add_f32_e32 v161, v161, v165
	v_add_f32_e32 v162, v162, v166
	v_add_f32_e32 v163, v163, v167
	ds_bpermute_b32 v164, v134, v160
	ds_bpermute_b32 v165, v134, v161
	ds_bpermute_b32 v166, v134, v162
	ds_bpermute_b32 v167, v134, v163
	s_waitcnt lgkmcnt(0)
	v_add_f32_e32 v160, v160, v164
	v_add_f32_e32 v161, v161, v165
	v_add_f32_e32 v162, v162, v166
	v_add_f32_e32 v163, v163, v167
	ds_bpermute_b32 v164, v135, v160
	ds_bpermute_b32 v165, v135, v161
	ds_bpermute_b32 v166, v135, v162
	ds_bpermute_b32 v167, v135, v163
	s_waitcnt lgkmcnt(0)
	v_add_f32_e32 v160, v160, v164
	v_add_f32_e32 v161, v161, v165
	v_add_f32_e32 v162, v162, v166
	v_add_f32_e32 v163, v163, v167
	v_cndmask_b32_e64 v164, 0, v160, s[12:13]
	v_cndmask_b32_e64 v165, 0, v161, s[12:13]
	v_cndmask_b32_e64 v166, 0, v162, s[12:13]
	v_cndmask_b32_e64 v167, 0, v163, s[12:13]
	s_mov_b64 exec, 0xffff
	global_store_dword v186, v164, s[6:7]
	global_store_dword v187, v165, s[6:7]
	global_store_dword v188, v166, s[6:7]
	global_store_dword v189, v167, s[6:7]
	s_mov_b64 exec, -1
	s_add_i32 s6, s3, 0x7000
	s_lshl_b32 s6, s6, 12
	s_add_u32 s4, s18, s6
	s_addc_u32 s5, s19, 0
	global_load_dwordx4 v[2:5], v140, s[4:5] nt
	global_load_dwordx4 v[6:9], v140, s[4:5] offset:1024 nt
	global_load_dwordx4 v[10:13], v140, s[4:5] offset:2048 nt
	global_load_dwordx4 v[14:17], v140, s[4:5] offset:3072 nt
	global_load_dwordx4 v[18:21], v141, s[4:5] nt
	global_load_dwordx4 v[22:25], v141, s[4:5] offset:1024 nt
	global_load_dwordx4 v[26:29], v141, s[4:5] offset:2048 nt
	global_load_dwordx4 v[30:33], v141, s[4:5] offset:3072 nt
	global_load_dwordx4 v[34:37], v142, s[4:5] nt
	global_load_dwordx4 v[38:41], v142, s[4:5] offset:1024 nt
	global_load_dwordx4 v[42:45], v142, s[4:5] offset:2048 nt
	global_load_dwordx4 v[46:49], v142, s[4:5] offset:3072 nt
	global_load_dwordx4 v[50:53], v143, s[4:5] nt
	global_load_dwordx4 v[54:57], v143, s[4:5] offset:1024 nt
	global_load_dwordx4 v[58:61], v143, s[4:5] offset:2048 nt
	global_load_dwordx4 v[62:65], v143, s[4:5] offset:3072 nt
	s_waitcnt vmcnt(36)
; __device__ void p0_xconv(const Args& a) {
;     ...
; #pragma unroll
;         for (int r = 0; r < 4; ++r) {
;             const int row = row0 + r * nwv;
;             if (row < MROWS) {
;                 float ss = 0.f;
; #pragma unroll
;                 for (int i = 0; i < 4; ++i) {
;                     const f32x4 x = v[r][i];
;                     ss += (x[0] * x[0] + x[1] * x[1]) + (x[2] * x[2] + x[3] * x[3]);
;                     f16x4 h; h[0] = (f16)x[0]; h[1] = (f16)x[1]; h[2] = (f16)x[2]; h[3] = (f16)x[3];
;                     *(f16x4*)(XH + (size_t)row * DM + i * 256 + lane * 4) = h;
;                 }
; #pragma unroll
;                 for (int o = 1; o < 64; o <<= 1) ss += __shfl_xor(ss, o);
	s_add_i32 s6, s3, 0xa000
	s_lshl_b32 s7, s6, 11
	s_add_u32 s10, s40, s7
	s_addc_u32 s11, s41, 0
	s_lshl_b32 s7, s6, 6
	s_add_u32 s6, s40, s7
	s_addc_u32 s7, s41, 0
	s_add_u32 s6, s6, 0x1f800000
	s_addc_u32 s7, s7, 0
	v_mul_f32_e32 v150, v67, v67
	v_mul_f32_e32 v151, v69, v69
	v_fmac_f32_e32 v150, v66, v66
	v_fmac_f32_e32 v151, v68, v68
	v_add_f32_e32 v160, v150, v151
	v_cvt_pk_f16_f32 v170, v66, v67
	v_cvt_pk_f16_f32 v171, v68, v69
	v_mul_f32_e32 v150, v71, v71
	v_mul_f32_e32 v151, v73, v73
	v_fmac_f32_e32 v150, v70, v70
	v_fmac_f32_e32 v151, v72, v72
	v_add_f32_e32 v152, v150, v151
	v_add_f32_e32 v160, v160, v152
	v_cvt_pk_f16_f32 v172, v70, v71
	v_cvt_pk_f16_f32 v173, v72, v73
	v_mul_f32_e32 v150, v75, v75
	v_mul_f32_e32 v151, v77, v77
	v_fmac_f32_e32 v150, v74, v74
	v_fmac_f32_e32 v151, v76, v76
	v_add_f32_e32 v152, v150, v151
	v_add_f32_e32 v160, v160, v152
	v_cvt_pk_f16_f32 v174, v74, v75
	v_cvt_pk_f16_f32 v175, v76, v77
	v_mul_f32_e32 v150, v79, v79
	v_mul_f32_e32 v151, v81, v81
	v_fmac_f32_e32 v150, v78, v78
	v_fmac_f32_e32 v151, v80, v80
	v_add_f32_e32 v152, v150, v151
	v_add_f32_e32 v160, v160, v152
	v_cvt_pk_f16_f32 v176, v78, v79
	v_cvt_pk_f16_f32 v177, v80, v81
	global_store_dwordx2 v144, v[170:171], s[10:11]
	global_store_dwordx2 v144, v[172:173], s[10:11] offset:512
	global_store_dwordx2 v144, v[174:175], s[10:11] offset:1024
	global_store_dwordx2 v144, v[176:177], s[10:11] offset:1536
	v_mul_f32_e32 v150, v83, v83
	v_mul_f32_e32 v151, v85, v85
	v_fmac_f32_e32 v150, v82, v82
	v_fmac_f32_e32 v151, v84, v84
	v_add_f32_e32 v161, v150, v151
	v_cvt_pk_f16_f32 v178, v82, v83
	v_cvt_pk_f16_f32 v179, v84, v85
	v_mul_f32_e32 v150, v87, v87
	v_mul_f32_e32 v151, v89, v89
	v_fmac_f32_e32 v150, v86, v86
	v_fmac_f32_e32 v151, v88, v88
	v_add_f32_e32 v152, v150, v151
	v_add_f32_e32 v161, v161, v152
	v_cvt_pk_f16_f32 v180, v86, v87
	v_cvt_pk_f16_f32 v181, v88, v89
	v_mul_f32_e32 v150, v91, v91
	v_mul_f32_e32 v151, v93, v93
	v_fmac_f32_e32 v150, v90, v90
	v_fmac_f32_e32 v151, v92, v92
	v_add_f32_e32 v152, v150, v151
	v_add_f32_e32 v161, v161, v152
	v_cvt_pk_f16_f32 v182, v90, v91
	v_cvt_pk_f16_f32 v183, v92, v93
	v_mul_f32_e32 v150, v95, v95
	v_mul_f32_e32 v151, v97, v97
	v_fmac_f32_e32 v150, v94, v94
	v_fmac_f32_e32 v151, v96, v96
	v_add_f32_e32 v152, v150, v151
	v_add_f32_e32 v161, v161, v152
	v_cvt_pk_f16_f32 v184, v94, v95
	v_cvt_pk_f16_f32 v185, v96, v97
	global_store_dwordx2 v145, v[178:179], s[10:11]
	global_store_dwordx2 v145, v[180:181], s[10:11] offset:512
	global_store_dwordx2 v145, v[182:183], s[10:11] offset:1024
	global_store_dwordx2 v145, v[184:185], s[10:11] offset:1536
	v_mul_f32_e32 v150, v99, v99
	v_mul_f32_e32 v151, v101, v101
	v_fmac_f32_e32 v150, v98, v98
	v_fmac_f32_e32 v151, v100, v100
	v_add_f32_e32 v162, v150, v151
	v_cvt_pk_f16_f32 v170, v98, v99
	v_cvt_pk_f16_f32 v171, v100, v101
	v_mul_f32_e32 v150, v103, v103
	v_mul_f32_e32 v151, v105, v105
	v_fmac_f32_e32 v150, v102, v102
	v_fmac_f32_e32 v151, v104, v104
	v_add_f32_e32 v152, v150, v151
	v_add_f32_e32 v162, v162, v152
	v_cvt_pk_f16_f32 v172, v102, v103
	v_cvt_pk_f16_f32 v173, v104, v105
	v_mul_f32_e32 v150, v107, v107
	v_mul_f32_e32 v151, v109, v109
	v_fmac_f32_e32 v150, v106, v106
	v_fmac_f32_e32 v151, v108, v108
	v_add_f32_e32 v152, v150, v151
	v_add_f32_e32 v162, v162, v152
	v_cvt_pk_f16_f32 v174, v106, v107
	v_cvt_pk_f16_f32 v175, v108, v109
	v_mul_f32_e32 v150, v111, v111
	v_mul_f32_e32 v151, v113, v113
	v_fmac_f32_e32 v150, v110, v110
	v_fmac_f32_e32 v151, v112, v112
	v_add_f32_e32 v152, v150, v151
	v_add_f32_e32 v162, v162, v152
	v_cvt_pk_f16_f32 v176, v110, v111
	v_cvt_pk_f16_f32 v177, v112, v113
	global_store_dwordx2 v146, v[170:171], s[10:11]
	global_store_dwordx2 v146, v[172:173], s[10:11] offset:512
	global_store_dwordx2 v146, v[174:175], s[10:11] offset:1024
	global_store_dwordx2 v146, v[176:177], s[10:11] offset:1536
	v_mul_f32_e32 v150, v115, v115
	v_mul_f32_e32 v151, v117, v117
	v_fmac_f32_e32 v150, v114, v114
	v_fmac_f32_e32 v151, v116, v116
	v_add_f32_e32 v163, v150, v151
	v_cvt_pk_f16_f32 v178, v114, v115
	v_cvt_pk_f16_f32 v179, v116, v117
	v_mul_f32_e32 v150, v119, v119
	v_mul_f32_e32 v151, v121, v121
	v_fmac_f32_e32 v150, v118, v118
	v_fmac_f32_e32 v151, v120, v120
	v_add_f32_e32 v152, v150, v151
	v_add_f32_e32 v163, v163, v152
	v_cvt_pk_f16_f32 v180, v118, v119
	v_cvt_pk_f16_f32 v181, v120, v121
	v_mul_f32_e32 v150, v123, v123
	v_mul_f32_e32 v151, v125, v125
	v_fmac_f32_e32 v150, v122, v122
	v_fmac_f32_e32 v151, v124, v124
	v_add_f32_e32 v152, v150, v151
	v_add_f32_e32 v163, v163, v152
	v_cvt_pk_f16_f32 v182, v122, v123
	v_cvt_pk_f16_f32 v183, v124, v125
	v_mul_f32_e32 v150, v127, v127
	v_mul_f32_e32 v151, v129, v129
	v_fmac_f32_e32 v150, v126, v126
	v_fmac_f32_e32 v151, v128, v128
	v_add_f32_e32 v152, v150, v151
	v_add_f32_e32 v163, v163, v152
	v_cvt_pk_f16_f32 v184, v126, v127
	v_cvt_pk_f16_f32 v185, v128, v129
	global_store_dwordx2 v147, v[178:179], s[10:11]
	global_store_dwordx2 v147, v[180:181], s[10:11] offset:512
	global_store_dwordx2 v147, v[182:183], s[10:11] offset:1024
	global_store_dwordx2 v147, v[184:185], s[10:11] offset:1536
	ds_bpermute_b32 v164, v130, v160
	ds_bpermute_b32 v165, v130, v161
	ds_bpermute_b32 v166, v130, v162
	ds_bpermute_b32 v167, v130, v163
	s_waitcnt lgkmcnt(0)
	v_add_f32_e32 v160, v160, v164
	v_add_f32_e32 v161, v161, v165
	v_add_f32_e32 v162, v162, v166
	v_add_f32_e32 v163, v163, v167
	ds_bpermute_b32 v164, v131, v160
	ds_bpermute_b32 v165, v131, v161
	ds_bpermute_b32 v166, v131, v162
	ds_bpermute_b32 v167, v131, v163
	s_waitcnt lgkmcnt(0)
; __device__ void p0_xconv(const Args& a) {
;     ...
; #pragma unroll
;         for (int r = 0; r < 4; ++r) {
;             const int row = row0 + r * nwv;
;             if (row < MROWS) {
;                 float ss = 0.f;
; #pragma unroll
;                 for (int i = 0; i < 4; ++i) {
;                     const f32x4 x = v[r][i];
;                     ss += (x[0] * x[0] + x[1] * x[1]) + (x[2] * x[2] + x[3] * x[3]);
;                     f16x4 h; h[0] = (f16)x[0]; h[1] = (f16)x[1]; h[2] = (f16)x[2]; h[3] = (f16)x[3];
;                     *(f16x4*)(XH + (size_t)row * DM + i * 256 + lane * 4) = h;
;                 }
;     ...
;                 for (int o = 1; o < 64; o <<= 1) ss += __shfl_xor(ss, o);
;                 if (lane < 16) SS[(size_t)row * 16 + lane] = (lane == 0) ? ss : 0.f;
	v_add_f32_e32 v160, v160, v164
	v_add_f32_e32 v161, v161, v165
	v_add_f32_e32 v162, v162, v166
	v_add_f32_e32 v163, v163, v167
	ds_bpermute_b32 v164, v132, v160
	ds_bpermute_b32 v165, v132, v161
	ds_bpermute_b32 v166, v132, v162
	ds_bpermute_b32 v167, v132, v163
	s_waitcnt lgkmcnt(0)
	v_add_f32_e32 v160, v160, v164
	v_add_f32_e32 v161, v161, v165
	v_add_f32_e32 v162, v162, v166
	v_add_f32_e32 v163, v163, v167
	ds_bpermute_b32 v164, v133, v160
	ds_bpermute_b32 v165, v133, v161
	ds_bpermute_b32 v166, v133, v162
	ds_bpermute_b32 v167, v133, v163
	s_waitcnt lgkmcnt(0)
	v_add_f32_e32 v160, v160, v164
	v_add_f32_e32 v161, v161, v165
	v_add_f32_e32 v162, v162, v166
	v_add_f32_e32 v163, v163, v167
	ds_bpermute_b32 v164, v134, v160
	ds_bpermute_b32 v165, v134, v161
	ds_bpermute_b32 v166, v134, v162
	ds_bpermute_b32 v167, v134, v163
	s_waitcnt lgkmcnt(0)
	v_add_f32_e32 v160, v160, v164
	v_add_f32_e32 v161, v161, v165
	v_add_f32_e32 v162, v162, v166
	v_add_f32_e32 v163, v163, v167
	ds_bpermute_b32 v164, v135, v160
	ds_bpermute_b32 v165, v135, v161
	ds_bpermute_b32 v166, v135, v162
	ds_bpermute_b32 v167, v135, v163
	s_waitcnt lgkmcnt(0)
	v_add_f32_e32 v160, v160, v164
	v_add_f32_e32 v161, v161, v165
	v_add_f32_e32 v162, v162, v166
	v_add_f32_e32 v163, v163, v167
	v_cndmask_b32_e64 v164, 0, v160, s[12:13]
	v_cndmask_b32_e64 v165, 0, v161, s[12:13]
	v_cndmask_b32_e64 v166, 0, v162, s[12:13]
	v_cndmask_b32_e64 v167, 0, v163, s[12:13]
	s_mov_b64 exec, 0xffff
	global_store_dword v186, v164, s[6:7]
	global_store_dword v187, v165, s[6:7]
	global_store_dword v188, v166, s[6:7]
	global_store_dword v189, v167, s[6:7]
	s_mov_b64 exec, -1
	s_waitcnt vmcnt(20)
	s_add_i32 s6, s3, 0xb000
	s_lshl_b32 s7, s6, 11
	s_add_u32 s10, s40, s7
	s_addc_u32 s11, s41, 0
	s_lshl_b32 s7, s6, 6
	s_add_u32 s6, s40, s7
	s_addc_u32 s7, s41, 0
	s_add_u32 s6, s6, 0x1f800000
	s_addc_u32 s7, s7, 0
	v_mul_f32_e32 v150, v3, v3
	v_mul_f32_e32 v151, v5, v5
	v_fmac_f32_e32 v150, v2, v2
	v_fmac_f32_e32 v151, v4, v4
	v_add_f32_e32 v160, v150, v151
	v_cvt_pk_f16_f32 v170, v2, v3
	v_cvt_pk_f16_f32 v171, v4, v5
	v_mul_f32_e32 v150, v7, v7
	v_mul_f32_e32 v151, v9, v9
	v_fmac_f32_e32 v150, v6, v6
	v_fmac_f32_e32 v151, v8, v8
	v_add_f32_e32 v152, v150, v151
	v_add_f32_e32 v160, v160, v152
	v_cvt_pk_f16_f32 v172, v6, v7
	v_cvt_pk_f16_f32 v173, v8, v9
	v_mul_f32_e32 v150, v11, v11
	v_mul_f32_e32 v151, v13, v13
	v_fmac_f32_e32 v150, v10, v10
	v_fmac_f32_e32 v151, v12, v12
	v_add_f32_e32 v152, v150, v151
	v_add_f32_e32 v160, v160, v152
	v_cvt_pk_f16_f32 v174, v10, v11
	v_cvt_pk_f16_f32 v175, v12, v13
	v_mul_f32_e32 v150, v15, v15
	v_mul_f32_e32 v151, v17, v17
	v_fmac_f32_e32 v150, v14, v14
	v_fmac_f32_e32 v151, v16, v16
	v_add_f32_e32 v152, v150, v151
	v_add_f32_e32 v160, v160, v152
	v_cvt_pk_f16_f32 v176, v14, v15
	v_cvt_pk_f16_f32 v177, v16, v17
	global_store_dwordx2 v144, v[170:171], s[10:11]
	global_store_dwordx2 v144, v[172:173], s[10:11] offset:512
	global_store_dwordx2 v144, v[174:175], s[10:11] offset:1024
	global_store_dwordx2 v144, v[176:177], s[10:11] offset:1536
	v_mul_f32_e32 v150, v19, v19
	v_mul_f32_e32 v151, v21, v21
	v_fmac_f32_e32 v150, v18, v18
	v_fmac_f32_e32 v151, v20, v20
	v_add_f32_e32 v161, v150, v151
	v_cvt_pk_f16_f32 v178, v18, v19
	v_cvt_pk_f16_f32 v179, v20, v21
	v_mul_f32_e32 v150, v23, v23
	v_mul_f32_e32 v151, v25, v25
	v_fmac_f32_e32 v150, v22, v22
	v_fmac_f32_e32 v151, v24, v24
	v_add_f32_e32 v152, v150, v151
	v_add_f32_e32 v161, v161, v152
	v_cvt_pk_f16_f32 v180, v22, v23
	v_cvt_pk_f16_f32 v181, v24, v25
	v_mul_f32_e32 v150, v27, v27
	v_mul_f32_e32 v151, v29, v29
	v_fmac_f32_e32 v150, v26, v26
	v_fmac_f32_e32 v151, v28, v28
	v_add_f32_e32 v152, v150, v151
	v_add_f32_e32 v161, v161, v152
	v_cvt_pk_f16_f32 v182, v26, v27
	v_cvt_pk_f16_f32 v183, v28, v29
	v_mul_f32_e32 v150, v31, v31
	v_mul_f32_e32 v151, v33, v33
	v_fmac_f32_e32 v150, v30, v30
	v_fmac_f32_e32 v151, v32, v32
	v_add_f32_e32 v152, v150, v151
	v_add_f32_e32 v161, v161, v152
	v_cvt_pk_f16_f32 v184, v30, v31
	v_cvt_pk_f16_f32 v185, v32, v33
	global_store_dwordx2 v145, v[178:179], s[10:11]
	global_store_dwordx2 v145, v[180:181], s[10:11] offset:512
	global_store_dwordx2 v145, v[182:183], s[10:11] offset:1024
	global_store_dwordx2 v145, v[184:185], s[10:11] offset:1536
	v_mul_f32_e32 v150, v35, v35
	v_mul_f32_e32 v151, v37, v37
	v_fmac_f32_e32 v150, v34, v34
	v_fmac_f32_e32 v151, v36, v36
	v_add_f32_e32 v162, v150, v151
	v_cvt_pk_f16_f32 v170, v34, v35
	v_cvt_pk_f16_f32 v171, v36, v37
	v_mul_f32_e32 v150, v39, v39
	v_mul_f32_e32 v151, v41, v41
	v_fmac_f32_e32 v150, v38, v38
	v_fmac_f32_e32 v151, v40, v40
	v_add_f32_e32 v152, v150, v151
	v_add_f32_e32 v162, v162, v152
	v_cvt_pk_f16_f32 v172, v38, v39
	v_cvt_pk_f16_f32 v173, v40, v41
	v_mul_f32_e32 v150, v43, v43
	v_mul_f32_e32 v151, v45, v45
	v_fmac_f32_e32 v150, v42, v42
	v_fmac_f32_e32 v151, v44, v44
	v_add_f32_e32 v152, v150, v151
	v_add_f32_e32 v162, v162, v152
	v_cvt_pk_f16_f32 v174, v42, v43
	v_cvt_pk_f16_f32 v175, v44, v45
	v_mul_f32_e32 v150, v47, v47
	v_mul_f32_e32 v151, v49, v49
	v_fmac_f32_e32 v150, v46, v46
	v_fmac_f32_e32 v151, v48, v48
	v_add_f32_e32 v152, v150, v151
	v_add_f32_e32 v162, v162, v152
	v_cvt_pk_f16_f32 v176, v46, v47
	v_cvt_pk_f16_f32 v177, v48, v49
	global_store_dwordx2 v146, v[170:171], s[10:11]
	global_store_dwordx2 v146, v[172:173], s[10:11] offset:512
	global_store_dwordx2 v146, v[174:175], s[10:11] offset:1024
	global_store_dwordx2 v146, v[176:177], s[10:11] offset:1536
	v_mul_f32_e32 v150, v51, v51
	v_mul_f32_e32 v151, v53, v53
	v_fmac_f32_e32 v150, v50, v50
	v_fmac_f32_e32 v151, v52, v52
	v_add_f32_e32 v163, v150, v151
	v_cvt_pk_f16_f32 v178, v50, v51
	v_cvt_pk_f16_f32 v179, v52, v53
	v_mul_f32_e32 v150, v55, v55
	v_mul_f32_e32 v151, v57, v57
	v_fmac_f32_e32 v150, v54, v54
	v_fmac_f32_e32 v151, v56, v56
	v_add_f32_e32 v152, v150, v151
	v_add_f32_e32 v163, v163, v152
	v_cvt_pk_f16_f32 v180, v54, v55
	v_cvt_pk_f16_f32 v181, v56, v57
	v_mul_f32_e32 v150, v59, v59
	v_mul_f32_e32 v151, v61, v61
	v_fmac_f32_e32 v150, v58, v58
	v_fmac_f32_e32 v151, v60, v60
	v_add_f32_e32 v152, v150, v151
	v_add_f32_e32 v163, v163, v152
	v_cvt_pk_f16_f32 v182, v58, v59
	v_cvt_pk_f16_f32 v183, v60, v61
	v_mul_f32_e32 v150, v63, v63
	v_mul_f32_e32 v151, v65, v65
	v_fmac_f32_e32 v150, v62, v62
	v_fmac_f32_e32 v151, v64, v64
	v_add_f32_e32 v152, v150, v151
	v_add_f32_e32 v163, v163, v152
	v_cvt_pk_f16_f32 v184, v62, v63
	v_cvt_pk_f16_f32 v185, v64, v65
	global_store_dwordx2 v147, v[178:179], s[10:11]
	global_store_dwordx2 v147, v[180:181], s[10:11] offset:512
	global_store_dwordx2 v147, v[182:183], s[10:11] offset:1024
	global_store_dwordx2 v147, v[184:185], s[10:11] offset:1536
	ds_bpermute_b32 v164, v130, v160
	ds_bpermute_b32 v165, v130, v161
	ds_bpermute_b32 v166, v130, v162
	ds_bpermute_b32 v167, v130, v163
	s_waitcnt lgkmcnt(0)
; __device__ void p0_xconv(const Args& a) {
;     f16* XH = (f16*)(a.ws + WS_XH); float* SS = (float*)(a.ws + WS_SS);
;     int tid_ = threadIdx.x; asm volatile("" : "+v"(tid_));
;     const int lane = tid_ & 63, wv = tid_ >> 6;
;     const int nwv = (int)gridDim.x * 8;
;     for (int row0 = (int)blockIdx.x * 8 + wv; row0 < MROWS; row0 += 4 * nwv) {
;     ...
;                 float ss = 0.f;
; #pragma unroll
;                 for (int i = 0; i < 4; ++i) {
;                     const f32x4 x = v[r][i];
;                     ss += (x[0] * x[0] + x[1] * x[1]) + (x[2] * x[2] + x[3] * x[3]);
;                     f16x4 h; h[0] = (f16)x[0]; h[1] = (f16)x[1]; h[2] = (f16)x[2]; h[3] = (f16)x[3];
;                     *(f16x4*)(XH + (size_t)row * DM + i * 256 + lane * 4) = h;
;                 }
; #pragma unroll
;                 for (int o = 1; o < 64; o <<= 1) ss += __shfl_xor(ss, o);
;                 if (lane < 16) SS[(size_t)row * 16 + lane] = (lane == 0) ? ss : 0.f;
	v_add_f32_e32 v160, v160, v164
	v_add_f32_e32 v161, v161, v165
	v_add_f32_e32 v162, v162, v166
	v_add_f32_e32 v163, v163, v167
	ds_bpermute_b32 v164, v131, v160
	ds_bpermute_b32 v165, v131, v161
	ds_bpermute_b32 v166, v131, v162
	ds_bpermute_b32 v167, v131, v163
	s_waitcnt lgkmcnt(0)
	v_add_f32_e32 v160, v160, v164
	v_add_f32_e32 v161, v161, v165
	v_add_f32_e32 v162, v162, v166
	v_add_f32_e32 v163, v163, v167
	ds_bpermute_b32 v164, v132, v160
	ds_bpermute_b32 v165, v132, v161
	ds_bpermute_b32 v166, v132, v162
	ds_bpermute_b32 v167, v132, v163
	s_waitcnt lgkmcnt(0)
	v_add_f32_e32 v160, v160, v164
	v_add_f32_e32 v161, v161, v165
	v_add_f32_e32 v162, v162, v166
	v_add_f32_e32 v163, v163, v167
	ds_bpermute_b32 v164, v133, v160
	ds_bpermute_b32 v165, v133, v161
	ds_bpermute_b32 v166, v133, v162
	ds_bpermute_b32 v167, v133, v163
	s_waitcnt lgkmcnt(0)
	v_add_f32_e32 v160, v160, v164
	v_add_f32_e32 v161, v161, v165
	v_add_f32_e32 v162, v162, v166
	v_add_f32_e32 v163, v163, v167
	ds_bpermute_b32 v164, v134, v160
	ds_bpermute_b32 v165, v134, v161
	ds_bpermute_b32 v166, v134, v162
	ds_bpermute_b32 v167, v134, v163
	s_waitcnt lgkmcnt(0)
	v_add_f32_e32 v160, v160, v164
	v_add_f32_e32 v161, v161, v165
	v_add_f32_e32 v162, v162, v166
	v_add_f32_e32 v163, v163, v167
	ds_bpermute_b32 v164, v135, v160
	ds_bpermute_b32 v165, v135, v161
	ds_bpermute_b32 v166, v135, v162
	ds_bpermute_b32 v167, v135, v163
	s_waitcnt lgkmcnt(0)
	v_add_f32_e32 v160, v160, v164
	v_add_f32_e32 v161, v161, v165
	v_add_f32_e32 v162, v162, v166
	v_add_f32_e32 v163, v163, v167
	v_cndmask_b32_e64 v164, 0, v160, s[12:13]
	v_cndmask_b32_e64 v165, 0, v161, s[12:13]
	v_cndmask_b32_e64 v166, 0, v162, s[12:13]
	v_cndmask_b32_e64 v167, 0, v163, s[12:13]
	s_mov_b64 exec, 0xffff
	global_store_dword v186, v164, s[6:7]
	global_store_dword v187, v165, s[6:7]
	global_store_dword v188, v166, s[6:7]
	global_store_dword v189, v167, s[6:7]
	s_mov_b64 exec, -1
	s_barrier
	s_branch .LBB0_112
.LBB0_91:
	v_mov_b32_e32 v1, v0
	s_barrier
	s_mov_b32 s3, 0xc000
	v_ashrrev_i32_e32 v2, 6, v1
	v_lshl_add_u32 v78, s2, 3, v2
	v_add_u32_e32 v78, 0x7000, v78
	v_cmp_gt_i32_e32 vcc, s3, v78
	s_and_saveexec_b64 s[20:21], vcc
	s_cbranch_execz .LBB0_111
	v_and_b32_e32 v1, 63, v1
	v_mov_b32_e32 v67, 0
	v_lshlrev_b32_e32 v66, 2, v1
	v_lshlrev_b32_e32 v2, 3, v1
	v_mov_b32_e32 v3, v67
	s_load_dword s36, s[4:5], 0x0
	v_lshl_add_u64 v[68:69], s[40:41], 0, v[2:3]
	v_lshl_add_u64 v[2:3], s[40:41], 0, v[66:67]
	s_mov_b64 s[4:5], 0x1f800000
	v_cmp_gt_u32_e32 vcc, 16, v1
	v_lshl_add_u64 v[70:71], v[2:3], 0, s[4:5]
	v_cmp_eq_u32_e64 s[4:5], 0, v1
	v_mbcnt_lo_u32_b32 v1, -1, 0
	v_mbcnt_hi_u32_b32 v2, -1, v1
	v_and_b32_e32 v1, 64, v2
	v_add_u32_e32 v3, 64, v1
	v_xor_b32_e32 v1, 1, v2
	v_cmp_lt_i32_e64 s[6:7], v1, v3
	v_xor_b32_e32 v4, 2, v2
	s_waitcnt lgkmcnt(0)
	s_lshl_b32 s9, s36, 3
	v_cndmask_b32_e64 v1, v2, v1, s[6:7]
	v_cmp_lt_i32_e64 s[6:7], v4, v3
	s_add_i32 s44, s9, s9
	v_lshlrev_b32_e32 v1, 2, v1
	v_cndmask_b32_e64 v4, v2, v4, s[6:7]
	v_lshlrev_b32_e32 v80, 2, v4
	v_xor_b32_e32 v4, 4, v2
	v_cmp_lt_i32_e64 s[6:7], v4, v3
	s_lshl_b32 s33, s36, 4
	s_mul_i32 s36, s36, 24
	v_cndmask_b32_e64 v4, v2, v4, s[6:7]
	v_lshlrev_b32_e32 v81, 2, v4
	v_xor_b32_e32 v4, 8, v2
	v_cmp_lt_i32_e64 s[6:7], v4, v3
	s_mov_b64 s[22:23], 0
	s_movk_i32 s37, 0x4000
	v_cndmask_b32_e64 v4, v2, v4, s[6:7]
	v_lshlrev_b32_e32 v82, 2, v4
	v_xor_b32_e32 v4, 16, v2
	v_cmp_lt_i32_e64 s[6:7], v4, v3
	v_mov_b32_e32 v85, s19
	v_mov_b32_e32 v86, s17
	v_cndmask_b32_e64 v4, v2, v4, s[6:7]
	v_lshlrev_b32_e32 v83, 2, v4
	v_xor_b32_e32 v4, 32, v2
	v_cmp_lt_i32_e64 s[6:7], v4, v3
	v_mov_b32_e32 v87, s18
	v_mov_b32_e32 v88, s16
	v_cndmask_b32_e64 v2, v2, v4, s[6:7]
	v_lshlrev_b32_e32 v84, 2, v2
	v_lshlrev_b32_e32 v66, 2, v66
	s_add_i32 s44, s44, s9
	s_mov_b32 s45, 0xbfff
	s_branch .LBB0_94
